# final RMSNorm loop: row loads batched, gain hoisted; short-conv elementwise loop hand-written, 4 elements per thread in flight
# speedup vs baseline: 1.0169x; 1.0003x over previous
.LBB0_453:
	v_mov_b32_e32 v0, v226
	s_mov_b64 s[4:5], 0x410000
	v_ashrrev_i32_e32 v1, 31, v0
	v_lshl_add_u64 v[24:25], s[52:53], 0, v[0:1]
	v_cmp_gt_u64_e32 vcc, s[4:5], v[24:25]
	s_and_saveexec_b64 s[4:5], vcc
	s_cbranch_execz .LBB0_452
	v_and_b32_e32 v2, 0xff, v226
	v_lshlrev_b32_e32 v4, 3, v2
	v_lshlrev_b32_e32 v2, 4, v2
	v_mov_b32_e32 v3, 0
	v_mov_b32_e32 v5, 0
	v_readlane_b32 s18, v252, 32
	v_readlane_b32 s19, v252, 33
	v_readlane_b32 s46, v255, 2
	v_readlane_b32 s47, v255, 3
	global_load_dwordx4 v[40:43], v2, s[50:51]
	global_load_dwordx4 v[44:47], v2, s[54:55]
	global_load_dwordx4 v[48:51], v2, s[56:57]
	s_mov_b32 s42, 0xfffff000
	s_mov_b32 s43, -1
	s_mov_b32 s44, 0xffffe000
	s_mov_b32 s45, -1
	s_movk_i32 s7, 0x4080
.Lcv_loop:
	s_mov_b64 s[26:27], 0x1000
	v_mov_b32_e32 v6, v24
	v_cmp_gt_u32_e32 vcc, 0x410000, v6
	s_and_saveexec_b64 s[38:39], vcc
	s_cbranch_execz .Lcv_ld_skip_0
	v_lshrrev_b32_e32 v132, 8, v6
	v_lshlrev_b32_e32 v8, 12, v132
	v_mov_b32_e32 v9, 0
	v_lshl_add_u64 v[8:9], s[18:19], 0, v[8:9]
	v_lshl_add_u64 v[8:9], v[8:9], 0, v[2:3]
	global_load_dwordx4 v[52:55], v[8:9], off
	v_mul_u32_u24_e32 v10, 0x3f81, v132
	v_lshrrev_b32_e32 v140, 25, v10
	v_mul_u32_u24_e32 v10, 0x810, v140
	v_sub_u32_e32 v136, v132, v10
	v_subrev_u32_e32 v10, 0x4080, v132
	v_lshlrev_b32_e32 v10, 13, v10
	v_mov_b32_e32 v11, 0
	v_lshl_add_u64 v[10:11], s[46:47], 0, v[10:11]
	v_lshl_add_u64 v[10:11], v[10:11], 0, v[2:3]
	v_lshl_add_u64 v[12:13], v[8:9], 0, s[42:43]
	v_lshl_add_u64 v[14:15], v[8:9], 0, s[44:45]
	v_cmp_gt_u32_e32 vcc, 0x4080, v132
	s_nop 1
	v_cndmask_b32_e32 v14, v10, v14, vcc
	v_cndmask_b32_e32 v15, v11, v15, vcc
	v_lshl_add_u64 v[10:11], v[10:11], 0, s[26:27]
	v_cndmask_b32_e32 v12, v10, v12, vcc
	v_cndmask_b32_e32 v13, v11, v13, vcc
	global_load_dwordx4 v[56:59], v[12:13], off
	global_load_dwordx4 v[60:63], v[14:15], off
	v_lshlrev_b32_e32 v8, 11, v132
	v_mov_b32_e32 v9, 0
	v_lshl_add_u64 v[8:9], s[28:29], 0, v[8:9]
	v_lshl_add_u64 v[8:9], v[8:9], 0, v[4:5]
	global_load_dwordx2 v[64:65], v[8:9], off
.Lcv_ld_skip_0:
	s_or_b64 exec, exec, s[38:39]
	v_add_u32_e32 v6, 0x20000, v24
	v_cmp_gt_u32_e32 vcc, 0x410000, v6
	s_and_saveexec_b64 s[38:39], vcc
	s_cbranch_execz .Lcv_ld_skip_1
	v_lshrrev_b32_e32 v133, 8, v6
	v_lshlrev_b32_e32 v8, 12, v133
	v_mov_b32_e32 v9, 0
	v_lshl_add_u64 v[8:9], s[18:19], 0, v[8:9]
	v_lshl_add_u64 v[8:9], v[8:9], 0, v[2:3]
	global_load_dwordx4 v[84:87], v[8:9], off
	v_mul_u32_u24_e32 v10, 0x3f81, v133
	v_lshrrev_b32_e32 v141, 25, v10
	v_mul_u32_u24_e32 v10, 0x810, v141
	v_sub_u32_e32 v137, v133, v10
	v_subrev_u32_e32 v10, 0x4080, v133
	v_lshlrev_b32_e32 v10, 13, v10
	v_mov_b32_e32 v11, 0
	v_lshl_add_u64 v[10:11], s[46:47], 0, v[10:11]
	v_lshl_add_u64 v[10:11], v[10:11], 0, v[2:3]
	v_lshl_add_u64 v[12:13], v[8:9], 0, s[42:43]
	v_lshl_add_u64 v[14:15], v[8:9], 0, s[44:45]
	v_cmp_gt_u32_e32 vcc, 0x4080, v133
	s_nop 1
	v_cndmask_b32_e32 v14, v10, v14, vcc
	v_cndmask_b32_e32 v15, v11, v15, vcc
	v_lshl_add_u64 v[10:11], v[10:11], 0, s[26:27]
	v_cndmask_b32_e32 v12, v10, v12, vcc
	v_cndmask_b32_e32 v13, v11, v13, vcc
	global_load_dwordx4 v[88:91], v[12:13], off
	global_load_dwordx4 v[92:95], v[14:15], off
	v_lshlrev_b32_e32 v8, 11, v133
	v_mov_b32_e32 v9, 0
	v_lshl_add_u64 v[8:9], s[28:29], 0, v[8:9]
	v_lshl_add_u64 v[8:9], v[8:9], 0, v[4:5]
	global_load_dwordx2 v[96:97], v[8:9], off
.Lcv_ld_skip_1:
	s_or_b64 exec, exec, s[38:39]
	v_add_u32_e32 v6, 0x40000, v24
	v_cmp_gt_u32_e32 vcc, 0x410000, v6
	s_and_saveexec_b64 s[38:39], vcc
	s_cbranch_execz .Lcv_ld_skip_2
	v_lshrrev_b32_e32 v134, 8, v6
	v_lshlrev_b32_e32 v8, 12, v134
	v_mov_b32_e32 v9, 0
	v_lshl_add_u64 v[8:9], s[18:19], 0, v[8:9]
	v_lshl_add_u64 v[8:9], v[8:9], 0, v[2:3]
	global_load_dwordx4 v[100:103], v[8:9], off
	v_mul_u32_u24_e32 v10, 0x3f81, v134
	v_lshrrev_b32_e32 v142, 25, v10
	v_mul_u32_u24_e32 v10, 0x810, v142
	v_sub_u32_e32 v138, v134, v10
	v_subrev_u32_e32 v10, 0x4080, v134
	v_lshlrev_b32_e32 v10, 13, v10
	v_mov_b32_e32 v11, 0
	v_lshl_add_u64 v[10:11], s[46:47], 0, v[10:11]
	v_lshl_add_u64 v[10:11], v[10:11], 0, v[2:3]
	v_lshl_add_u64 v[12:13], v[8:9], 0, s[42:43]
	v_lshl_add_u64 v[14:15], v[8:9], 0, s[44:45]
	v_cmp_gt_u32_e32 vcc, 0x4080, v134
	s_nop 1
	v_cndmask_b32_e32 v14, v10, v14, vcc
	v_cndmask_b32_e32 v15, v11, v15, vcc
	v_lshl_add_u64 v[10:11], v[10:11], 0, s[26:27]
	v_cndmask_b32_e32 v12, v10, v12, vcc
	v_cndmask_b32_e32 v13, v11, v13, vcc
	global_load_dwordx4 v[104:107], v[12:13], off
	global_load_dwordx4 v[108:111], v[14:15], off
	v_lshlrev_b32_e32 v8, 11, v134
	v_mov_b32_e32 v9, 0
	v_lshl_add_u64 v[8:9], s[28:29], 0, v[8:9]
	v_lshl_add_u64 v[8:9], v[8:9], 0, v[4:5]
	global_load_dwordx2 v[112:113], v[8:9], off
.Lcv_ld_skip_2:
	s_or_b64 exec, exec, s[38:39]
	v_add_u32_e32 v6, 0x60000, v24
	v_cmp_gt_u32_e32 vcc, 0x410000, v6
	s_and_saveexec_b64 s[38:39], vcc
	s_cbranch_execz .Lcv_ld_skip_3
	v_lshrrev_b32_e32 v135, 8, v6
	v_lshlrev_b32_e32 v8, 12, v135
	v_mov_b32_e32 v9, 0
	v_lshl_add_u64 v[8:9], s[18:19], 0, v[8:9]
	v_lshl_add_u64 v[8:9], v[8:9], 0, v[2:3]
	global_load_dwordx4 v[116:119], v[8:9], off
	v_mul_u32_u24_e32 v10, 0x3f81, v135
	v_lshrrev_b32_e32 v143, 25, v10
	v_mul_u32_u24_e32 v10, 0x810, v143
	v_sub_u32_e32 v139, v135, v10
	v_subrev_u32_e32 v10, 0x4080, v135
	v_lshlrev_b32_e32 v10, 13, v10
	v_mov_b32_e32 v11, 0
	v_lshl_add_u64 v[10:11], s[46:47], 0, v[10:11]
	v_lshl_add_u64 v[10:11], v[10:11], 0, v[2:3]
	v_lshl_add_u64 v[12:13], v[8:9], 0, s[42:43]
	v_lshl_add_u64 v[14:15], v[8:9], 0, s[44:45]
	v_cmp_gt_u32_e32 vcc, 0x4080, v135
	s_nop 1
	v_cndmask_b32_e32 v14, v10, v14, vcc
	v_cndmask_b32_e32 v15, v11, v15, vcc
	v_lshl_add_u64 v[10:11], v[10:11], 0, s[26:27]
	v_cndmask_b32_e32 v12, v10, v12, vcc
	v_cndmask_b32_e32 v13, v11, v13, vcc
	global_load_dwordx4 v[120:123], v[12:13], off
	global_load_dwordx4 v[124:127], v[14:15], off
	v_lshlrev_b32_e32 v8, 11, v135
	v_mov_b32_e32 v9, 0
	v_lshl_add_u64 v[8:9], s[28:29], 0, v[8:9]
	v_lshl_add_u64 v[8:9], v[8:9], 0, v[4:5]
	global_load_dwordx2 v[128:129], v[8:9], off
.Lcv_ld_skip_3:
	s_or_b64 exec, exec, s[38:39]
	s_waitcnt vmcnt(0)
	v_mov_b32_e32 v6, v24
	v_cmp_gt_u32_e32 vcc, 0x410000, v6
	s_and_saveexec_b64 s[38:39], vcc
	s_cbranch_execz .Lcv_cp_skip_0
	v_cmp_gt_u32_e64 s[12:13], s7, v132
	v_cmp_gt_u32_e32 vcc, 1, v136
	s_nop 1
	s_and_b64 vcc, vcc, s[12:13]
	v_cndmask_b32_e64 v56, v56, 0, vcc
	v_cndmask_b32_e64 v57, v57, 0, vcc
	v_cndmask_b32_e64 v58, v58, 0, vcc
	v_cndmask_b32_e64 v59, v59, 0, vcc
	v_cmp_gt_u32_e32 vcc, 2, v136
	s_nop 1
	s_and_b64 vcc, vcc, s[12:13]
	v_cndmask_b32_e64 v60, v60, 0, vcc
	v_cndmask_b32_e64 v61, v61, 0, vcc
	v_cndmask_b32_e64 v62, v62, 0, vcc
	v_cndmask_b32_e64 v63, v63, 0, vcc
	v_pk_mul_f32 v[8:9], v[40:41], v[60:61]
	v_pk_mul_f32 v[10:11], v[42:43], v[62:63]
	v_pk_fma_f32 v[8:9], v[44:45], v[56:57], v[8:9]
	v_pk_fma_f32 v[10:11], v[46:47], v[58:59], v[10:11]
	v_pk_fma_f32 v[8:9], v[48:49], v[52:53], v[8:9]
	v_pk_fma_f32 v[10:11], v[50:51], v[54:55], v[10:11]
	v_lshlrev_b32_e32 v12, 16, v64
	v_and_b32_e32 v13, 0xffff0000, v64
	v_lshlrev_b32_e32 v14, 16, v65
	v_and_b32_e32 v15, 0xffff0000, v65
	v_mul_f32_e32 v8, v8, v12
	v_mul_f32_e32 v9, v9, v13
	v_mul_f32_e32 v10, v10, v14
	v_mul_f32_e32 v11, v11, v15
	v_cvt_pk_bf16_f32 v8, v8, v9
	v_cvt_pk_bf16_f32 v9, v10, v11
	v_lshlrev_b32_e32 v12, 11, v132
	v_mov_b32_e32 v13, 0
	v_lshl_add_u64 v[12:13], s[48:49], 0, v[12:13]
	v_lshl_add_u64 v[12:13], v[12:13], 0, v[4:5]
	global_store_dwordx2 v[12:13], v[8:9], off
	s_mov_b64 s[26:27], exec
	s_andn2_b64 exec, exec, s[12:13]
	s_cbranch_execz .Lcv_nosamp_0
	v_subrev_u32_e32 v14, 0x4080, v132
	v_lshlrev_b32_e32 v14, 13, v14
	v_mov_b32_e32 v15, 0
	v_lshl_add_u64 v[14:15], s[58:59], 0, v[14:15]
	v_lshl_add_u64 v[14:15], v[14:15], 0, v[2:3]
	s_mov_b64 s[12:13], 0x1000
	v_lshl_add_u64 v[16:17], v[14:15], 0, s[12:13]
	global_store_dwordx4 v[14:15], v[56:59], off
	global_store_dwordx4 v[16:17], v[52:55], off
.Lcv_nosamp_0:
	s_mov_b64 exec, s[26:27]
	v_cmp_gt_u32_e64 s[12:13], s7, v132
	v_cmp_lt_u32_e32 vcc, 0x80d, v136
	s_nop 1
	s_and_b64 vcc, vcc, s[12:13]
	s_and_b64 exec, exec, vcc
	s_cbranch_execz .Lcv_nocvp_0
	v_lshl_add_u32 v14, v140, 1, v136
	v_add_u32_e32 v14, 0xfffff7f2, v14
	v_lshlrev_b32_e32 v14, 12, v14
	v_mov_b32_e32 v15, 0
	v_lshl_add_u64 v[14:15], s[60:61], 0, v[14:15]
	v_lshl_add_u64 v[14:15], v[14:15], 0, v[2:3]
	global_store_dwordx4 v[14:15], v[52:55], off
.Lcv_nocvp_0:
	s_mov_b64 exec, s[26:27]
.Lcv_cp_skip_0:
	s_or_b64 exec, exec, s[38:39]
	v_add_u32_e32 v6, 0x20000, v24
	v_cmp_gt_u32_e32 vcc, 0x410000, v6
	s_and_saveexec_b64 s[38:39], vcc
	s_cbranch_execz .Lcv_cp_skip_1
	v_cmp_gt_u32_e64 s[12:13], s7, v133
	v_cmp_gt_u32_e32 vcc, 1, v137
	s_nop 1
	s_and_b64 vcc, vcc, s[12:13]
	v_cndmask_b32_e64 v88, v88, 0, vcc
	v_cndmask_b32_e64 v89, v89, 0, vcc
	v_cndmask_b32_e64 v90, v90, 0, vcc
	v_cndmask_b32_e64 v91, v91, 0, vcc
	v_cmp_gt_u32_e32 vcc, 2, v137
	s_nop 1
	s_and_b64 vcc, vcc, s[12:13]
	v_cndmask_b32_e64 v92, v92, 0, vcc
	v_cndmask_b32_e64 v93, v93, 0, vcc
	v_cndmask_b32_e64 v94, v94, 0, vcc
	v_cndmask_b32_e64 v95, v95, 0, vcc
	v_pk_mul_f32 v[8:9], v[40:41], v[92:93]
	v_pk_mul_f32 v[10:11], v[42:43], v[94:95]
	v_pk_fma_f32 v[8:9], v[44:45], v[88:89], v[8:9]
	v_pk_fma_f32 v[10:11], v[46:47], v[90:91], v[10:11]
	v_pk_fma_f32 v[8:9], v[48:49], v[84:85], v[8:9]
	v_pk_fma_f32 v[10:11], v[50:51], v[86:87], v[10:11]
	v_lshlrev_b32_e32 v12, 16, v96
	v_and_b32_e32 v13, 0xffff0000, v96
	v_lshlrev_b32_e32 v14, 16, v97
	v_and_b32_e32 v15, 0xffff0000, v97
	v_mul_f32_e32 v8, v8, v12
	v_mul_f32_e32 v9, v9, v13
	v_mul_f32_e32 v10, v10, v14
	v_mul_f32_e32 v11, v11, v15
	v_cvt_pk_bf16_f32 v8, v8, v9
	v_cvt_pk_bf16_f32 v9, v10, v11
	v_lshlrev_b32_e32 v12, 11, v133
	v_mov_b32_e32 v13, 0
	v_lshl_add_u64 v[12:13], s[48:49], 0, v[12:13]
	v_lshl_add_u64 v[12:13], v[12:13], 0, v[4:5]
	global_store_dwordx2 v[12:13], v[8:9], off
	s_mov_b64 s[26:27], exec
	s_andn2_b64 exec, exec, s[12:13]
	s_cbranch_execz .Lcv_nosamp_1
	v_subrev_u32_e32 v14, 0x4080, v133
	v_lshlrev_b32_e32 v14, 13, v14
	v_mov_b32_e32 v15, 0
	v_lshl_add_u64 v[14:15], s[58:59], 0, v[14:15]
	v_lshl_add_u64 v[14:15], v[14:15], 0, v[2:3]
	s_mov_b64 s[12:13], 0x1000
	v_lshl_add_u64 v[16:17], v[14:15], 0, s[12:13]
	global_store_dwordx4 v[14:15], v[88:91], off
	global_store_dwordx4 v[16:17], v[84:87], off
.Lcv_nosamp_1:
	s_mov_b64 exec, s[26:27]
	v_cmp_gt_u32_e64 s[12:13], s7, v133
	v_cmp_lt_u32_e32 vcc, 0x80d, v137
	s_nop 1
	s_and_b64 vcc, vcc, s[12:13]
	s_and_b64 exec, exec, vcc
	s_cbranch_execz .Lcv_nocvp_1
	v_lshl_add_u32 v14, v141, 1, v137
	v_add_u32_e32 v14, 0xfffff7f2, v14
	v_lshlrev_b32_e32 v14, 12, v14
	v_mov_b32_e32 v15, 0
	v_lshl_add_u64 v[14:15], s[60:61], 0, v[14:15]
	v_lshl_add_u64 v[14:15], v[14:15], 0, v[2:3]
	global_store_dwordx4 v[14:15], v[84:87], off

.Lcv_cp_skip_1:
	s_or_b64 exec, exec, s[38:39]
	v_add_u32_e32 v6, 0x40000, v24
	v_cmp_gt_u32_e32 vcc, 0x410000, v6
	s_and_saveexec_b64 s[38:39], vcc
	s_cbranch_execz .Lcv_cp_skip_2
	v_cmp_gt_u32_e64 s[12:13], s7, v134
	v_cmp_gt_u32_e32 vcc, 1, v138
	s_nop 1
	s_and_b64 vcc, vcc, s[12:13]
	v_cndmask_b32_e64 v104, v104, 0, vcc
	v_cndmask_b32_e64 v105, v105, 0, vcc
	v_cndmask_b32_e64 v106, v106, 0, vcc
	v_cndmask_b32_e64 v107, v107, 0, vcc
	v_cmp_gt_u32_e32 vcc, 2, v138
	s_nop 1
	s_and_b64 vcc, vcc, s[12:13]
	v_cndmask_b32_e64 v108, v108, 0, vcc
	v_cndmask_b32_e64 v109, v109, 0, vcc
	v_cndmask_b32_e64 v110, v110, 0, vcc
	v_cndmask_b32_e64 v111, v111, 0, vcc
	v_pk_mul_f32 v[8:9], v[40:41], v[108:109]
	v_pk_mul_f32 v[10:11], v[42:43], v[110:111]
	v_pk_fma_f32 v[8:9], v[44:45], v[104:105], v[8:9]
	v_pk_fma_f32 v[10:11], v[46:47], v[106:107], v[10:11]
	v_pk_fma_f32 v[8:9], v[48:49], v[100:101], v[8:9]
	v_pk_fma_f32 v[10:11], v[50:51], v[102:103], v[10:11]
	v_lshlrev_b32_e32 v12, 16, v112
	v_and_b32_e32 v13, 0xffff0000, v112
	v_lshlrev_b32_e32 v14, 16, v113
	v_and_b32_e32 v15, 0xffff0000, v113
	v_mul_f32_e32 v8, v8, v12
	v_mul_f32_e32 v9, v9, v13
	v_mul_f32_e32 v10, v10, v14
	v_mul_f32_e32 v11, v11, v15
	v_cvt_pk_bf16_f32 v8, v8, v9
	v_cvt_pk_bf16_f32 v9, v10, v11
	v_lshlrev_b32_e32 v12, 11, v134
	v_mov_b32_e32 v13, 0
	v_lshl_add_u64 v[12:13], s[48:49], 0, v[12:13]
	v_lshl_add_u64 v[12:13], v[12:13], 0, v[4:5]
	global_store_dwordx2 v[12:13], v[8:9], off
	s_mov_b64 s[26:27], exec
	s_andn2_b64 exec, exec, s[12:13]
	s_cbranch_execz .Lcv_nosamp_2
	v_subrev_u32_e32 v14, 0x4080, v134
	v_lshlrev_b32_e32 v14, 13, v14
	v_mov_b32_e32 v15, 0
	v_lshl_add_u64 v[14:15], s[58:59], 0, v[14:15]
	v_lshl_add_u64 v[14:15], v[14:15], 0, v[2:3]
	s_mov_b64 s[12:13], 0x1000
	v_lshl_add_u64 v[16:17], v[14:15], 0, s[12:13]
	global_store_dwordx4 v[14:15], v[104:107], off
	global_store_dwordx4 v[16:17], v[100:103], off
.Lcv_nosamp_2:
	s_mov_b64 exec, s[26:27]
	v_cmp_gt_u32_e64 s[12:13], s7, v134
	v_cmp_lt_u32_e32 vcc, 0x80d, v138
	s_nop 1
	s_and_b64 vcc, vcc, s[12:13]
	s_and_b64 exec, exec, vcc
	s_cbranch_execz .Lcv_nocvp_2
	v_lshl_add_u32 v14, v142, 1, v138
	v_add_u32_e32 v14, 0xfffff7f2, v14
	v_lshlrev_b32_e32 v14, 12, v14
	v_mov_b32_e32 v15, 0
	v_lshl_add_u64 v[14:15], s[60:61], 0, v[14:15]
	v_lshl_add_u64 v[14:15], v[14:15], 0, v[2:3]
	global_store_dwordx4 v[14:15], v[100:103], off

.Lcv_cp_skip_2:
	s_or_b64 exec, exec, s[38:39]
	v_add_u32_e32 v6, 0x60000, v24
	v_cmp_gt_u32_e32 vcc, 0x410000, v6
	s_and_saveexec_b64 s[38:39], vcc
	s_cbranch_execz .Lcv_cp_skip_3
	v_cmp_gt_u32_e64 s[12:13], s7, v135
	v_cmp_gt_u32_e32 vcc, 1, v139
	s_nop 1
	s_and_b64 vcc, vcc, s[12:13]
	v_cndmask_b32_e64 v120, v120, 0, vcc
	v_cndmask_b32_e64 v121, v121, 0, vcc
	v_cndmask_b32_e64 v122, v122, 0, vcc
	v_cndmask_b32_e64 v123, v123, 0, vcc
	v_cmp_gt_u32_e32 vcc, 2, v139
	s_nop 1
	s_and_b64 vcc, vcc, s[12:13]
	v_cndmask_b32_e64 v124, v124, 0, vcc
	v_cndmask_b32_e64 v125, v125, 0, vcc
	v_cndmask_b32_e64 v126, v126, 0, vcc
	v_cndmask_b32_e64 v127, v127, 0, vcc
	v_pk_mul_f32 v[8:9], v[40:41], v[124:125]
	v_pk_mul_f32 v[10:11], v[42:43], v[126:127]
	v_pk_fma_f32 v[8:9], v[44:45], v[120:121], v[8:9]
	v_pk_fma_f32 v[10:11], v[46:47], v[122:123], v[10:11]
	v_pk_fma_f32 v[8:9], v[48:49], v[116:117], v[8:9]
	v_pk_fma_f32 v[10:11], v[50:51], v[118:119], v[10:11]
	v_lshlrev_b32_e32 v12, 16, v128
	v_and_b32_e32 v13, 0xffff0000, v128
	v_lshlrev_b32_e32 v14, 16, v129
	v_and_b32_e32 v15, 0xffff0000, v129
	v_mul_f32_e32 v8, v8, v12
	v_mul_f32_e32 v9, v9, v13
	v_mul_f32_e32 v10, v10, v14
	v_mul_f32_e32 v11, v11, v15
	v_cvt_pk_bf16_f32 v8, v8, v9
	v_cvt_pk_bf16_f32 v9, v10, v11
	v_lshlrev_b32_e32 v12, 11, v135
	v_mov_b32_e32 v13, 0
	v_lshl_add_u64 v[12:13], s[48:49], 0, v[12:13]
	v_lshl_add_u64 v[12:13], v[12:13], 0, v[4:5]
	global_store_dwordx2 v[12:13], v[8:9], off
	s_mov_b64 s[26:27], exec
	s_andn2_b64 exec, exec, s[12:13]
	s_cbranch_execz .Lcv_nosamp_3
	v_subrev_u32_e32 v14, 0x4080, v135
	v_lshlrev_b32_e32 v14, 13, v14
	v_mov_b32_e32 v15, 0
	v_lshl_add_u64 v[14:15], s[58:59], 0, v[14:15]
	v_lshl_add_u64 v[14:15], v[14:15], 0, v[2:3]
	s_mov_b64 s[12:13], 0x1000
	v_lshl_add_u64 v[16:17], v[14:15], 0, s[12:13]
	global_store_dwordx4 v[14:15], v[120:123], off
	global_store_dwordx4 v[16:17], v[116:119], off
.Lcv_nosamp_3:
	s_mov_b64 exec, s[26:27]
	v_cmp_gt_u32_e64 s[12:13], s7, v135
	v_cmp_lt_u32_e32 vcc, 0x80d, v139
	s_nop 1
	s_and_b64 vcc, vcc, s[12:13]
	s_and_b64 exec, exec, vcc
	s_cbranch_execz .Lcv_nocvp_3
	v_lshl_add_u32 v14, v143, 1, v139
	v_add_u32_e32 v14, 0xfffff7f2, v14
	v_lshlrev_b32_e32 v14, 12, v14
	v_mov_b32_e32 v15, 0
	v_lshl_add_u64 v[14:15], s[60:61], 0, v[14:15]
	v_lshl_add_u64 v[14:15], v[14:15], 0, v[2:3]
	global_store_dwordx4 v[14:15], v[116:119], off

.Lcv_cp_skip_3:
	s_or_b64 exec, exec, s[38:39]
	v_add_u32_e32 v24, 0x80000, v24
	v_cmp_gt_u32_e32 vcc, 0x410000, v24
	s_cbranch_vccnz .Lcv_loop
	s_branch .LBB0_452

.LBB0_3475:
	s_andn2_b64 vcc, exec, s[18:19]
	s_cbranch_vccnz .LBB0_3451
	v_readlane_b32 s18, v252, 30
	v_readlane_b32 s19, v252, 31
	s_andn2_b64 vcc, exec, s[18:19]
	s_cbranch_vccnz .LBB0_3451
	v_readlane_b32 s18, v250, 0
	v_readlane_b32 s19, v250, 1
	s_load_dwordx2 s[18:19], s[18:19], 0x50
	v_readlane_b32 s26, v254, 42
	v_lshlrev_b32_e32 v80, 4, v148
	v_readlane_b32 s27, v254, 43
	v_readlane_b32 s7, v254, 29
	v_lshlrev_b32_e32 v24, 4, v148
	v_lshl_add_u64 v[16:17], s[26:27], 0, v[80:81]
	s_waitcnt lgkmcnt(0)
	v_lshl_add_u64 v[18:19], s[18:19], 0, v[80:81]
	s_mov_b32 s18, s7
	global_load_dwordx4 v[84:87], v[18:19], off
	global_load_dwordx4 v[88:91], v[18:19], off offset:1024
	global_load_dwordx4 v[92:95], v[18:19], off offset:2048
	global_load_dwordx4 v[96:99], v[18:19], off offset:3072
	s_waitcnt vmcnt(0)
	s_branch .LBB0_3479

.LBB0_3483:
	s_andn2_b64 vcc, exec, s[42:43]
	s_cbranch_vccnz .LBB0_3478
	global_load_dwordx4 v[4:7], v[16:17], off offset:-3072
	global_load_dwordx4 v[12:15], v[16:17], off offset:-2048
	global_load_dwordx4 v[8:11], v[16:17], off offset:-1024
	global_load_dwordx4 v[0:3], v[16:17], off
	s_waitcnt vmcnt(3)
	v_pk_mul_f32 v[28:29], v[6:7], v[6:7]
	v_pk_mul_f32 v[30:31], v[4:5], v[4:5]
	s_nop 0
	v_pk_mov_b32 v[32:33], v[30:31], v[28:29] op_sel:[1,0]
	v_mov_b32_e32 v31, v29
	v_pk_add_f32 v[20:21], v[32:33], v[30:31]
	s_waitcnt vmcnt(2)
	v_pk_mul_f32 v[28:29], v[14:15], v[14:15]
	v_pk_mul_f32 v[30:31], v[12:13], v[12:13]
	v_pk_add_f32 v[20:21], v[20:21], v[20:21] op_sel:[0,1] op_sel_hi:[1,0]
	v_pk_mov_b32 v[32:33], v[30:31], v[28:29] op_sel:[1,0]
	v_mov_b32_e32 v31, v29
	v_pk_add_f32 v[22:23], v[32:33], v[30:31]
	s_nop 0
	v_pk_add_f32 v[22:23], v[22:23], v[22:23] op_sel:[0,1] op_sel_hi:[1,0]
	s_waitcnt vmcnt(0)
	v_mul_f32_e32 v25, v0, v0
	v_mul_f32_e32 v26, v1, v1
	v_mov_b32_e32 v21, v25
	v_mov_b32_e32 v23, v26
	v_pk_add_f32 v[20:21], v[20:21], v[22:23]
	v_mul_f32_e32 v22, v9, v9
	v_mul_f32_e32 v27, v2, v2
	v_pk_fma_f32 v[22:23], v[8:9], v[8:9], v[22:23] op_sel_hi:[1,1,0]
	v_mul_f32_e32 v26, v11, v11
	v_mul_f32_e32 v28, v3, v3
	v_mov_b32_e32 v23, v27
	v_pk_fma_f32 v[26:27], v[10:11], v[10:11], v[26:27] op_sel_hi:[1,1,0]
	s_nop 0
	v_mov_b32_e32 v27, v28
	v_pk_add_f32 v[22:23], v[22:23], v[26:27]
	s_nop 0
	v_pk_add_f32 v[20:21], v[20:21], v[22:23]
	v_xor_b32_e32 v22, 1, v235
	v_add_f32_e32 v20, v20, v21
	v_and_b32_e32 v21, 64, v235
	v_add_u32_e32 v21, 64, v21
	v_cmp_lt_i32_e32 vcc, v22, v21
	s_nop 1
	v_cndmask_b32_e32 v22, v235, v22, vcc
	v_lshlrev_b32_e32 v22, 2, v22
	ds_bpermute_b32 v22, v22, v20
	s_waitcnt lgkmcnt(0)
	v_add_f32_e32 v20, v20, v22
	v_xor_b32_e32 v22, 2, v235
	v_cmp_lt_i32_e32 vcc, v22, v21
	s_nop 1
	v_cndmask_b32_e32 v22, v235, v22, vcc
	v_lshlrev_b32_e32 v22, 2, v22
	ds_bpermute_b32 v22, v22, v20
	s_waitcnt lgkmcnt(0)
	v_add_f32_e32 v20, v20, v22
	v_xor_b32_e32 v22, 4, v235
	v_cmp_lt_i32_e32 vcc, v22, v21
	s_nop 1
	v_cndmask_b32_e32 v22, v235, v22, vcc
	v_lshlrev_b32_e32 v22, 2, v22
	ds_bpermute_b32 v22, v22, v20
	s_waitcnt lgkmcnt(0)
	v_add_f32_e32 v20, v20, v22
	v_xor_b32_e32 v22, 8, v235
	v_cmp_lt_i32_e32 vcc, v22, v21
	s_nop 1
	v_cndmask_b32_e32 v22, v235, v22, vcc
	v_lshlrev_b32_e32 v22, 2, v22
	ds_bpermute_b32 v22, v22, v20
	s_waitcnt lgkmcnt(0)
	v_add_f32_e32 v20, v20, v22
	v_xor_b32_e32 v22, 16, v235
	v_cmp_lt_i32_e32 vcc, v22, v21
	s_nop 1
	v_cndmask_b32_e32 v22, v235, v22, vcc
	v_lshlrev_b32_e32 v22, 2, v22
	ds_bpermute_b32 v22, v22, v20
	s_waitcnt lgkmcnt(0)
	v_add_f32_e32 v20, v20, v22
	v_xor_b32_e32 v22, 32, v235
	v_cmp_lt_i32_e32 vcc, v22, v21
	s_nop 1
	v_cndmask_b32_e32 v21, v235, v22, vcc
	v_lshlrev_b32_e32 v21, 2, v21
	ds_bpermute_b32 v21, v21, v20
	s_waitcnt lgkmcnt(0)
	v_add_f32_e32 v20, v20, v21
	v_fmamk_f32 v20, v20, 0x3a800000, v231
	v_cmp_gt_f32_e32 vcc, s48, v20
	v_mul_f32_e32 v21, 0x4f800000, v20
	s_nop 0
	v_cndmask_b32_e32 v20, v20, v21, vcc
	v_sqrt_f32_e32 v21, v20
	s_nop 0
	v_add_u32_e32 v22, -1, v21
	v_fma_f32 v23, -v22, v21, v20
	v_cmp_ge_f32_e64 s[42:43], 0, v23
	v_add_u32_e32 v23, 1, v21
	s_nop 0
	v_cndmask_b32_e64 v22, v21, v22, s[42:43]
	v_fma_f32 v21, -v23, v21, v20
	v_cmp_lt_f32_e64 s[42:43], 0, v21
	s_nop 1
	v_cndmask_b32_e64 v21, v22, v23, s[42:43]
	v_mul_f32_e32 v22, 0x37800000, v21
	v_cndmask_b32_e32 v21, v21, v22, vcc
	v_cmp_class_f32_e32 vcc, v20, v230
	s_nop 1
	v_cndmask_b32_e32 v20, v21, v20, vcc
	v_div_scale_f32 v21, s[26:27], v20, v20, 1.0
	v_rcp_f32_e32 v22, v21
	s_nop 0
	v_fma_f32 v23, -v21, v22, 1.0
	v_fmac_f32_e32 v22, v23, v22
	v_div_scale_f32 v23, vcc, 1.0, v20, 1.0
	v_mul_f32_e32 v25, v23, v22
	v_fma_f32 v26, -v21, v25, v23
	v_fmac_f32_e32 v25, v26, v22
	v_fma_f32 v21, -v21, v25, v23
	v_div_fmas_f32 v21, v21, v22, v25
	v_div_fixup_f32 v20, v21, v20, 1.0
	v_pk_mul_f32 v[22:23], v[4:5], v[20:21] op_sel_hi:[1,0]
	v_pk_mul_f32 v[26:27], v[6:7], v[20:21] op_sel_hi:[1,0]
	s_nop 0
	v_pk_mul_f32 v[6:7], v[86:87], v[26:27]
	v_pk_mul_f32 v[4:5], v[84:85], v[22:23]
	v_pk_mul_f32 v[22:23], v[12:13], v[20:21] op_sel_hi:[1,0]
	v_pk_mul_f32 v[26:27], v[14:15], v[20:21] op_sel_hi:[1,0]
	s_nop 0
	v_pk_mul_f32 v[14:15], v[90:91], v[26:27]
	v_pk_mul_f32 v[12:13], v[88:89], v[22:23]
	v_pk_mul_f32 v[22:23], v[8:9], v[20:21] op_sel_hi:[1,0]
	v_pk_mul_f32 v[26:27], v[10:11], v[20:21] op_sel_hi:[1,0]
	s_nop 0
	v_pk_mul_f32 v[8:9], v[92:93], v[22:23]
	v_pk_mul_f32 v[22:23], v[0:1], v[20:21] op_sel_hi:[1,0]
	v_pk_mul_f32 v[20:21], v[2:3], v[20:21] op_sel_hi:[1,0]
	v_pk_mul_f32 v[10:11], v[94:95], v[26:27]
	s_nop 0
	v_pk_mul_f32 v[2:3], v[98:99], v[20:21]
	v_pk_mul_f32 v[0:1], v[96:97], v[22:23]
	global_store_dwordx4 v24, v[4:7], s[44:45]
	global_store_dwordx4 v24, v[12:15], s[44:45] offset:1024
	global_store_dwordx4 v24, v[8:11], s[44:45] offset:2048
	global_store_dwordx4 v24, v[0:3], s[44:45] offset:3072
	s_branch .LBB0_3478
